# attention item: accumulators cleared with 64-bit moves (20 instead of 40 instructions per item)
# baseline (speedup 1.0000x reference)
.LBB0_361:
	ds_read_b128 v[178:181], v194 offset:0
	ds_read_b128 v[182:185], v194 offset:64
	ds_read_b128 v[186:189], v194 offset:2304
	ds_read_b128 v[190:193], v194 offset:2368
	ds_read_b64_tr_b16 v[200:201], v195 offset:0
	ds_read_b64_tr_b16 v[202:203], v195 offset:2304
	ds_read_b64_tr_b16 v[204:205], v195 offset:32
	ds_read_b64_tr_b16 v[206:207], v195 offset:2336
	ds_read_b64_tr_b16 v[208:209], v195 offset:64
	ds_read_b64_tr_b16 v[210:211], v195 offset:2368
	ds_read_b64_tr_b16 v[212:213], v195 offset:96
	ds_read_b64_tr_b16 v[214:215], v195 offset:2400
	v_lshrrev_b32_e32 v15, 3, v0
	v_and_b32_e32 v16, 7, v0
	v_lshlrev_b32_e32 v16, 4, v16
	v_mad_u32_u24 v196, v15, s95, v16
	v_and_b32_e32 v16, 48, v0
	v_mad_u32_u24 v198, v17, s95, v16
	s_lshl_b32 s60, s95, 6
	s_lshl_b32 s61, s95, 4
	s_sub_i32 s93, 4, s92
	s_max_i32 s93, s93, 0
	s_cmp_eq_u32 s17, 0
	s_cselect_b32 s93, 0, s93
	v_mov_b64_e32 v[138:139], 0
	v_mov_b64_e32 v[140:141], 0
	v_mov_b64_e32 v[118:119], 0
	v_mov_b64_e32 v[120:121], 0
	v_mov_b64_e32 v[134:135], 0
	v_mov_b64_e32 v[136:137], 0
	v_mov_b64_e32 v[130:131], 0
	v_mov_b64_e32 v[132:133], 0
	v_mov_b64_e32 v[126:127], 0
	v_mov_b64_e32 v[128:129], 0
	v_mov_b64_e32 v[122:123], 0
	v_mov_b64_e32 v[124:125], 0
	v_mov_b64_e32 v[114:115], 0
	v_mov_b64_e32 v[116:117], 0
	v_mov_b64_e32 v[106:107], 0
	v_mov_b64_e32 v[108:109], 0
	v_mov_b64_e32 v[110:111], 0
	v_mov_b64_e32 v[112:113], 0
	v_mov_b64_e32 v[102:103], 0
	v_mov_b64_e32 v[104:105], 0
	s_waitcnt lgkmcnt(8)
	v_mfma_f32_16x16x32_bf16 v[150:153], v[178:181], v[74:77], v[66:69]
	v_mfma_f32_16x16x32_bf16 v[154:157], v[186:189], v[74:77], v[66:69]
	v_mfma_f32_16x16x32_bf16 v[162:165], v[186:189], v[82:85], v[66:69]
	v_mfma_f32_16x16x32_bf16 v[150:153], v[182:185], v[70:73], v[150:153]
	v_mfma_f32_16x16x32_bf16 v[154:157], v[190:193], v[70:73], v[154:157]
	v_mfma_f32_16x16x32_bf16 v[162:165], v[190:193], v[78:81], v[162:165]
	s_waitcnt lgkmcnt(0)
	ds_read_b128 v[178:181], v194 offset:4608
	ds_read_b128 v[182:185], v194 offset:4672
	ds_read_b128 v[186:189], v194 offset:6912
	ds_read_b128 v[190:193], v194 offset:6976
	ds_read_b64_tr_b16 v[216:217], v195 offset:4608
	ds_read_b64_tr_b16 v[218:219], v195 offset:6912
	ds_read_b64_tr_b16 v[220:221], v195 offset:4640
	ds_read_b64_tr_b16 v[222:223], v195 offset:6944
	ds_read_b64_tr_b16 v[224:225], v195 offset:4672
	ds_read_b64_tr_b16 v[226:227], v195 offset:6976
	ds_read_b64_tr_b16 v[228:229], v195 offset:4704
	ds_read_b64_tr_b16 v[230:231], v195 offset:7008
